# top-k: bit loop without the empty upper-half candidates when qb<64; item loop: running list pointers with sentinel entries, reference read as float from a table published by the forced pass
# speedup vs baseline: 1.0228x; 1.0027x over previous
.LBB0_1332:
	s_cmp_lt_i32 s44, 64
	s_cbranch_scc1 .Ltk_lo
.Ltk_hi:
	s_lshl_b32 s55, 1, s50
	s_or_b32 s32, s55, s54
	s_or_b32 s58, s55, s75
	s_or_b32 s59, s55, s74
	s_or_b32 s60, s55, s97
	v_cmp_le_u32_e32 vcc, s32, v8
	v_cmp_le_u32_e64 s[4:5], s32, v9
	v_cmp_le_u32_e64 s[24:25], s58, v6
	v_cmp_le_u32_e64 s[56:57], s58, v7
	v_cmp_le_u32_e64 s[98:99], s59, v4
	v_cmp_le_u32_e64 s[100:101], s59, v5
	s_bcnt1_i32_b64 s61, vcc
	s_bcnt1_i32_b64 s4, s[4:5]
	s_add_i32 s61, s61, s4
	v_cmp_le_u32_e32 vcc, s60, v2
	v_cmp_le_u32_e64 s[4:5], s60, v3
	s_cmp_gt_u32 s61, 15
	s_cselect_b32 s54, s32, s54
	s_cmp_eq_u32 s61, 16
	s_cselect_b32 s61, 1, 0
	s_or_b32 s51, s51, s61
	s_bcnt1_i32_b64 s24, s[24:25]
	s_bcnt1_i32_b64 s56, s[56:57]
	s_add_i32 s24, s24, s56
	s_cmp_gt_u32 s24, 15
	s_cselect_b32 s75, s58, s75
	s_cmp_eq_u32 s24, 16
	s_cselect_b32 s24, 2, 0
	s_or_b32 s51, s51, s24
	s_bcnt1_i32_b64 s98, s[98:99]
	s_bcnt1_i32_b64 s100, s[100:101]
	s_add_i32 s98, s98, s100
	s_cmp_gt_u32 s98, 15
	s_cselect_b32 s74, s59, s74
	s_cmp_eq_u32 s98, 16
	s_cselect_b32 s98, 4, 0
	s_or_b32 s51, s51, s98
	s_bcnt1_i32_b64 s61, vcc
	s_bcnt1_i32_b64 s4, s[4:5]
	s_add_i32 s61, s61, s4
	s_cmp_gt_u32 s61, 15
	s_cselect_b32 s97, s60, s97
	s_cmp_eq_u32 s61, 16
	s_cselect_b32 s61, 8, 0
	s_or_b32 s51, s51, s61
	s_add_i32 s50, s50, -1
	s_cmp_lg_u32 s51, 15
	s_cselect_b32 s61, 1, 0
	s_cmp_gt_i32 s50, -1
	s_cselect_b32 s4, 1, 0
	s_and_b32 s4, s4, s61
	s_cmp_lg_u32 s4, 0
	s_cbranch_scc1 .Ltk_hi
	s_branch .Ltk_done
.Ltk_lo:
	s_lshl_b32 s55, 1, s50
	s_or_b32 s32, s55, s54
	s_or_b32 s58, s55, s75
	s_or_b32 s59, s55, s74
	s_or_b32 s60, s55, s97
	v_cmp_le_u32_e32 vcc, s32, v8
	v_cmp_le_u32_e64 s[24:25], s58, v6
	v_cmp_le_u32_e64 s[98:99], s59, v4
	v_cmp_le_u32_e64 s[4:5], s60, v2
	s_nop 0
	s_bcnt1_i32_b64 s61, vcc
	s_cmp_gt_u32 s61, 15
	s_cselect_b32 s54, s32, s54
	s_cmp_eq_u32 s61, 16
	s_cselect_b32 s61, 1, 0
	s_or_b32 s51, s51, s61
	s_bcnt1_i32_b64 s24, s[24:25]
	s_cmp_gt_u32 s24, 15
	s_cselect_b32 s75, s58, s75
	s_cmp_eq_u32 s24, 16
	s_cselect_b32 s24, 2, 0
	s_or_b32 s51, s51, s24
	s_bcnt1_i32_b64 s98, s[98:99]
	s_cmp_gt_u32 s98, 15
	s_cselect_b32 s74, s59, s74
	s_cmp_eq_u32 s98, 16
	s_cselect_b32 s98, 4, 0
	s_or_b32 s51, s51, s98
	s_bcnt1_i32_b64 s61, s[4:5]
	s_cmp_gt_u32 s61, 15
	s_cselect_b32 s97, s60, s97
	s_cmp_eq_u32 s61, 16
	s_cselect_b32 s61, 8, 0
	s_or_b32 s51, s51, s61
	s_add_i32 s50, s50, -1
	s_cmp_lg_u32 s51, 15
	s_cselect_b32 s61, 1, 0
	s_cmp_gt_i32 s50, -1
	s_cselect_b32 s4, 1, 0
	s_and_b32 s4, s4, s61
	s_cmp_lg_u32 s4, 0
	s_cbranch_scc1 .Ltk_lo
.Ltk_done:
.LBB0_1333:
	v_cmp_lt_u32_e32 vcc, s54, v8
	v_cmp_lt_u32_e64 s[24:25], s54, v9
	s_bcnt1_i32_b64 s4, vcc
	s_bcnt1_i32_b64 s5, s[24:25]
	s_xor_b64 s[50:51], s[52:53], -1
	s_add_i32 s4, s5, s4
	v_cmp_eq_u32_e64 s[56:57], s54, v8
	v_cmp_eq_u32_e64 s[54:55], s54, v9
	s_and_b64 s[52:53], s[48:49], exec
	s_cselect_b32 s53, s55, 0
	s_cselect_b32 s52, s54, 0
	s_or_b64 s[24:25], s[52:53], s[24:25]
	s_and_b64 s[52:53], s[48:49], exec
	s_cselect_b32 s53, s57, 0
	s_cselect_b32 s52, s56, 0
	s_or_b64 s[52:53], s[52:53], vcc
	s_cmp_gt_u32 s4, 15
	s_cselect_b64 s[58:59], -1, 0
	s_or_b64 s[58:59], s[48:49], s[58:59]
	s_or_b64 s[60:61], s[54:55], s[56:57]
	s_cmp_eq_u64 s[60:61], 0
	s_cselect_b64 s[60:61], -1, 0
	s_or_b64 s[58:59], s[60:61], s[58:59]
	s_and_b64 vcc, exec, s[58:59]
	s_cbranch_vccnz .LBB0_1341
	s_sub_i32 s4, 16, s4
	s_cmp_eq_u64 s[56:57], 0
	s_cbranch_scc1 .LBB0_1337

.Lfe_done:
	s_nop 7
	s_nop 7
	v_mov_b32_e32 v191, v1
	v_mov_b32_e32 v192, v162
	v_mov_b64_e32 v[146:147], v[2:3]
	v_mov_b64_e32 v[148:149], v[4:5]
	v_mov_b64_e32 v[150:151], v[6:7]
	v_mov_b64_e32 v[152:153], v[8:9]
	v_mov_b64_e32 v[154:155], v[10:11]
	v_mov_b64_e32 v[156:157], v[12:13]
	v_mov_b64_e32 v[158:159], v[14:15]
	v_mov_b64_e32 v[160:161], v[16:17]
	v_mov_b64_e32 v[162:163], v[18:19]
	v_mov_b64_e32 v[164:165], v[20:21]
	v_mov_b64_e32 v[166:167], v[22:23]
	v_mov_b64_e32 v[168:169], v[24:25]
	v_mov_b64_e32 v[170:171], v[26:27]
	v_mov_b64_e32 v[172:173], v[28:29]
	v_mov_b64_e32 v[174:175], v[30:31]
	v_mov_b64_e32 v[176:177], v[32:33]
	s_and_saveexec_b64 s[12:13], s[8:9]
	s_cbranch_execz .LBB0_1399
	v_not_b32_e32 v3, v192
	v_or_b32_e32 v4, 0x80000000, v192
	v_cmp_gt_i32_e32 vcc, 0, v192
	v_add_u32_e32 v2, 0x10400, v183
	v_add_f32_e32 v5, 0xc1200000, v192
	v_cndmask_b32_e32 v3, v4, v3, vcc
	ds_write_b32 v2, v3
	ds_write_b32 v2, v5 offset:2304
.LBB0_1399:
	s_or_b64 exec, exec, s[12:13]
	s_add_u32 s4, s16, s42
	s_addc_u32 s5, s17, s43
	s_add_u32 s50, s4, 0x4200000
	s_addc_u32 s51, s5, 0
	s_waitcnt lgkmcnt(0)
	s_barrier
	s_cmp_gt_i32 s52, 0
	v_lshrrev_b32_e32 v2, 1, v210
	s_cselect_b64 s[20:21], -1, 0
	s_cmp_lt_i32 s52, 1
	v_add_u32_e32 v1, 0, v212
	v_add_u32_e32 v184, s87, v228
	v_and_b32_e32 v185, 16, v2
	s_cbranch_scc1 .LBB0_1424
	v_mov_b32_e32 v2, s86
	ds_read_b32 v2, v2
	v_add_u32_e32 v188, s91, v185
	s_mov_b32 s53, -1
	s_waitcnt lgkmcnt(0)
	v_readfirstlane_b32 s26, v2
	s_lshl_b32 s4, s26, 13
	s_and_b32 s12, s4, 0x1fe000
	s_add_u32 s4, s48, s12
	s_addc_u32 s5, s49, 0
	s_add_u32 s12, s50, s12
	s_addc_u32 s13, s51, 0
	global_load_dwordx4 v[50:53], v194, s[4:5]
	global_load_dwordx4 v[54:57], v194, s[4:5] offset:1024
	global_load_dwordx4 v[58:61], v194, s[4:5] offset:2048
	global_load_dwordx4 v[62:65], v194, s[4:5] offset:3072
	global_load_dwordx4 v[66:69], v200, s[4:5]
	global_load_dwordx4 v[78:81], v202, s[4:5]
	global_load_dwordx4 v[90:93], v204, s[4:5]
	global_load_dwordx4 v[98:101], v206, s[4:5]
	global_load_dwordx4 v[74:77], v194, s[12:13]
	global_load_dwordx4 v[70:73], v194, s[12:13] offset:1024
	global_load_dwordx4 v[86:89], v194, s[12:13] offset:2048
	global_load_dwordx4 v[82:85], v194, s[12:13] offset:3072
	global_load_dwordx4 v[94:97], v200, s[12:13]
	global_load_dwordx4 v[102:105], v202, s[12:13]
	global_load_dwordx4 v[106:109], v204, s[12:13]
	global_load_dwordx4 v[110:113], v206, s[12:13]
	s_lshl_b32 s4, s52, 2
	s_add_i32 s4, s86, s4
	v_mov_b32_e32 v132, s4
	v_add_u32_e32 v137, -4, v132
	ds_read_b32 v133, v137
	v_mov_b32_e32 v141, 0xc1200000
	s_add_i32 s99, s86, 4
	v_mov_b32_e32 v134, v184
	s_waitcnt lgkmcnt(0)
	ds_write2_b32 v132, v133, v133 offset1:1
	v_mov_b32_e32 v132, s99
	ds_read_b32 v133, v132
	ds_read_u8 v135, v134
	s_and_b32 s54, s26, 0xff
	s_add_i32 s99, s99, 4
	v_add_u32_e32 v134, 8, v134
	s_waitcnt lgkmcnt(0)
	v_readfirstlane_b32 s55, v133
	v_cmp_ne_u16_sdwa s[58:59], v135, s79 src0_sel:BYTE_0 src1_sel:DWORD
	s_and_b32 s4, s55, 0xff
	s_cmp_eq_u32 s4, s54
	s_cselect_b64 s[56:57], -1, 0
	v_cndmask_b32_e64 v135, 0, v135, s[58:59]
	v_and_b32_e32 v136, 63, v135
	v_lshl_or_b32 v130, v136, 2, v227
	v_mad_u32_u24 v137, v130, s66, v188
	ds_read_b128 v[114:117], v137
	ds_read_b128 v[118:121], v137 offset:32
	ds_read_b128 v[122:125], v137 offset:64
	ds_read_b128 v[126:129], v137 offset:96
	v_lshlrev_b32_e32 v138, 2, v130
	v_add_u32_e32 v138, 0x10d00, v138
	ds_read_b32 v139, v138
	s_waitcnt lgkmcnt(0)
	s_branch .Lit_commit
.Lit_top:
	v_mov_b32_e32 v132, s99
	ds_read_b32 v133, v132
	ds_read_u8 v135, v134
	s_and_b32 s54, s26, 0xff
	s_add_i32 s99, s99, 4
	v_add_u32_e32 v134, 8, v134
	v_cndmask_b32_e64 v140, v141, v139, s[14:15]
	s_waitcnt lgkmcnt(0)
	v_readfirstlane_b32 s55, v133
	v_cmp_ne_u16_sdwa s[58:59], v135, s79 src0_sel:BYTE_0 src1_sel:DWORD
	s_and_b32 s4, s55, 0xff
	s_cmp_eq_u32 s4, s54
	s_cselect_b64 s[56:57], -1, 0
	v_cndmask_b32_e64 v135, 0, v135, s[58:59]
	v_and_b32_e32 v136, 63, v135
	v_lshl_or_b32 v130, v136, 2, v227
	v_mad_u32_u24 v137, v130, s66, v188
	ds_read_b128 v[114:117], v137
	ds_read_b128 v[118:121], v137 offset:32
	ds_read_b128 v[122:125], v137 offset:64
	ds_read_b128 v[126:129], v137 offset:96
	v_lshlrev_b32_e32 v138, 2, v130
	v_add_u32_e32 v138, 0x10d00, v138
	ds_read_b32 v139, v138
	s_and_b64 vcc, exec, s[16:17]
	s_cbranch_vccnz .Lit_far
	s_sub_i32 s4, s44, s22
	v_lshl_add_u32 v34, s4, 6, v46
	s_nop 0
	v_sub_u32_e32 v34, v34, v181
	v_add_u32_e32 v36, -1, v34
	v_add_u32_e32 v38, -2, v34
	v_add_u32_e32 v40, -3, v34
	v_add_u32_e32 v42, -8, v34
	v_add_u32_e32 v44, -9, v34
	v_add_u32_e32 v46, -10, v34
	v_add_u32_e32 v48, -11, v34
	v_med3_i32 v35, v34, 0, v220
	v_med3_i32 v37, v36, 0, v220
	v_med3_i32 v39, v38, 0, v220
	v_med3_i32 v41, v40, 0, v220
	v_med3_i32 v43, v42, 0, v220
	v_med3_i32 v45, v44, 0, v220
	v_med3_i32 v47, v46, 0, v220
	v_med3_i32 v49, v48, 0, v220
	v_lshl_add_u32 v35, v35, 2, v180
	v_lshl_add_u32 v37, v37, 2, v180
	v_lshl_add_u32 v39, v39, 2, v180
	v_lshl_add_u32 v41, v41, 2, v180
	v_lshl_add_u32 v43, v43, 2, v180
	v_lshl_add_u32 v45, v45, 2, v180
	v_lshl_add_u32 v47, v47, 2, v180
	v_lshl_add_u32 v49, v49, 2, v180
	ds_read_b32 v35, v35
	ds_read_b32 v37, v37
	ds_read_b32 v39, v39
	ds_read_b32 v41, v41
	ds_read_b32 v43, v43
	ds_read_b32 v45, v45
	ds_read_b32 v47, v47
	ds_read_b32 v49, v49
	s_waitcnt lgkmcnt(7)
	v_add_f32_e32 v18, v18, v35
	v_cmp_lt_i32_e32 vcc, -1, v34
	v_mul_f32_e32 v18, 0x3fb8aa3b, v18
	s_and_b64 vcc, s[14:15], vcc
	v_cndmask_b32_e32 v18, v219, v18, vcc
	s_waitcnt lgkmcnt(6)
	v_add_f32_e32 v19, v19, v37
	v_cmp_lt_i32_e32 vcc, -1, v36
	v_mul_f32_e32 v19, 0x3fb8aa3b, v19
	s_and_b64 vcc, s[14:15], vcc
	v_cndmask_b32_e32 v19, v219, v19, vcc
	s_waitcnt lgkmcnt(5)
	v_add_f32_e32 v20, v20, v39
	v_cmp_lt_i32_e32 vcc, -1, v38
	v_mul_f32_e32 v20, 0x3fb8aa3b, v20
	s_and_b64 vcc, s[14:15], vcc
	v_cndmask_b32_e32 v20, v219, v20, vcc
	s_waitcnt lgkmcnt(4)
	v_add_f32_e32 v21, v21, v41
	v_cmp_lt_i32_e32 vcc, -1, v40
	v_mul_f32_e32 v21, 0x3fb8aa3b, v21
	s_and_b64 vcc, s[14:15], vcc
	v_cndmask_b32_e32 v21, v219, v21, vcc
	s_waitcnt lgkmcnt(3)
	v_add_f32_e32 v22, v22, v43
	v_cmp_lt_i32_e32 vcc, -1, v42
	v_mul_f32_e32 v22, 0x3fb8aa3b, v22
	s_and_b64 vcc, s[14:15], vcc
	v_cndmask_b32_e32 v22, v219, v22, vcc
	s_waitcnt lgkmcnt(2)
	v_add_f32_e32 v23, v23, v45
	v_cmp_lt_i32_e32 vcc, -1, v44
	v_mul_f32_e32 v23, 0x3fb8aa3b, v23
	s_and_b64 vcc, s[14:15], vcc
	v_cndmask_b32_e32 v23, v219, v23, vcc
	s_waitcnt lgkmcnt(1)
	v_add_f32_e32 v24, v24, v47
	v_cmp_lt_i32_e32 vcc, -1, v46
	v_mul_f32_e32 v24, 0x3fb8aa3b, v24
	s_and_b64 vcc, s[14:15], vcc
	s_waitcnt lgkmcnt(0)
	v_add_f32_e32 v25, v25, v49
	v_add_u32_e32 v35, -16, v34
	v_subrev_u32_e32 v37, 17, v34
	v_subrev_u32_e32 v39, 18, v34
	v_subrev_u32_e32 v41, 19, v34
	v_subrev_u32_e32 v43, 24, v34
	v_subrev_u32_e32 v45, 25, v34
	v_subrev_u32_e32 v47, 26, v34
	v_subrev_u32_e32 v49, 27, v34
	v_cndmask_b32_e32 v24, v219, v24, vcc
	v_cmp_lt_i32_e32 vcc, -1, v48
	v_med3_i32 v36, v35, 0, v220
	v_med3_i32 v38, v37, 0, v220
	v_med3_i32 v40, v39, 0, v220
	v_med3_i32 v42, v41, 0, v220
	v_med3_i32 v44, v43, 0, v220
	v_med3_i32 v46, v45, 0, v220
	v_med3_i32 v48, v47, 0, v220
	v_med3_i32 v190, v49, 0, v220
	v_mul_f32_e32 v25, 0x3fb8aa3b, v25
	s_and_b64 vcc, s[14:15], vcc
	v_lshl_add_u32 v36, v36, 2, v180
	v_lshl_add_u32 v38, v38, 2, v180
	v_lshl_add_u32 v40, v40, 2, v180
	v_lshl_add_u32 v42, v42, 2, v180
	v_lshl_add_u32 v44, v44, 2, v180
	v_lshl_add_u32 v46, v46, 2, v180
	v_lshl_add_u32 v48, v48, 2, v180
	v_lshl_add_u32 v190, v190, 2, v180
	v_cndmask_b32_e32 v25, v219, v25, vcc
	ds_read_b32 v36, v36
	ds_read_b32 v38, v38
	ds_read_b32 v40, v40
	ds_read_b32 v42, v42
	ds_read_b32 v44, v44
	ds_read_b32 v46, v46
	ds_read_b32 v48, v48
	ds_read_b32 v190, v190
	s_waitcnt lgkmcnt(7)
	v_add_f32_e32 v26, v26, v36
	v_cmp_lt_i32_e32 vcc, -1, v35
	v_mul_f32_e32 v26, 0x3fb8aa3b, v26
	s_and_b64 vcc, s[14:15], vcc
	v_cndmask_b32_e32 v26, v219, v26, vcc
	s_waitcnt lgkmcnt(6)
	v_add_f32_e32 v27, v27, v38
	v_cmp_lt_i32_e32 vcc, -1, v37
	v_mul_f32_e32 v27, 0x3fb8aa3b, v27
	s_and_b64 vcc, s[14:15], vcc
	v_cndmask_b32_e32 v27, v219, v27, vcc
	s_waitcnt lgkmcnt(5)
	v_add_f32_e32 v28, v28, v40
	v_cmp_lt_i32_e32 vcc, -1, v39
	v_mul_f32_e32 v28, 0x3fb8aa3b, v28
	s_and_b64 vcc, s[14:15], vcc
	v_cndmask_b32_e32 v28, v219, v28, vcc
	s_waitcnt lgkmcnt(4)
	v_add_f32_e32 v29, v29, v42
	v_cmp_lt_i32_e32 vcc, -1, v41
	v_mul_f32_e32 v29, 0x3fb8aa3b, v29
	s_and_b64 vcc, s[14:15], vcc
	v_cndmask_b32_e32 v29, v219, v29, vcc
	s_waitcnt lgkmcnt(3)
	v_add_f32_e32 v30, v30, v44
	v_cmp_lt_i32_e32 vcc, -1, v43
	v_mul_f32_e32 v30, 0x3fb8aa3b, v30
	s_and_b64 vcc, s[14:15], vcc
	v_cndmask_b32_e32 v30, v219, v30, vcc
	s_waitcnt lgkmcnt(2)
	v_add_f32_e32 v31, v31, v46
	v_cmp_lt_i32_e32 vcc, -1, v45
	v_mul_f32_e32 v31, 0x3fb8aa3b, v31
	s_and_b64 vcc, s[14:15], vcc
	v_cndmask_b32_e32 v31, v219, v31, vcc
	s_waitcnt lgkmcnt(1)
	v_add_f32_e32 v32, v32, v48
	v_cmp_lt_i32_e32 vcc, -1, v47
	v_mul_f32_e32 v32, 0x3fb8aa3b, v32
	s_and_b64 vcc, s[14:15], vcc
	v_cndmask_b32_e32 v32, v219, v32, vcc
	v_cmp_lt_i32_e32 vcc, -1, v49
	v_subrev_u32_e32 v35, 32, v34
	v_subrev_u32_e32 v37, 33, v34
	v_subrev_u32_e32 v39, 34, v34
	v_subrev_u32_e32 v41, 35, v34
	v_subrev_u32_e32 v43, 40, v34
	v_subrev_u32_e32 v45, 41, v34
	v_subrev_u32_e32 v47, 42, v34
	v_subrev_u32_e32 v49, 43, v34
	s_waitcnt lgkmcnt(0)
	v_add_f32_e32 v33, v33, v190
	v_med3_i32 v36, v35, 0, v220
	v_med3_i32 v38, v37, 0, v220
	v_med3_i32 v40, v39, 0, v220
	v_med3_i32 v42, v41, 0, v220
	v_med3_i32 v44, v43, 0, v220
	v_med3_i32 v46, v45, 0, v220
	v_med3_i32 v48, v47, 0, v220
	v_med3_i32 v190, v49, 0, v220
	v_mul_f32_e32 v33, 0x3fb8aa3b, v33
	s_and_b64 vcc, s[14:15], vcc
	v_lshl_add_u32 v36, v36, 2, v180
	v_lshl_add_u32 v38, v38, 2, v180
	v_lshl_add_u32 v40, v40, 2, v180
	v_lshl_add_u32 v42, v42, 2, v180
	v_lshl_add_u32 v44, v44, 2, v180
	v_lshl_add_u32 v46, v46, 2, v180
	v_lshl_add_u32 v48, v48, 2, v180
	v_lshl_add_u32 v190, v190, 2, v180
	v_cndmask_b32_e32 v33, v219, v33, vcc
	ds_read_b32 v36, v36
	ds_read_b32 v38, v38
	ds_read_b32 v40, v40
	ds_read_b32 v42, v42
	ds_read_b32 v44, v44
	ds_read_b32 v46, v46
	ds_read_b32 v48, v48
	ds_read_b32 v190, v190
	s_waitcnt lgkmcnt(7)
	v_add_f32_e32 v2, v2, v36
	v_cmp_lt_i32_e32 vcc, -1, v35
	v_mul_f32_e32 v2, 0x3fb8aa3b, v2
	s_and_b64 vcc, s[14:15], vcc
	v_cndmask_b32_e32 v2, v219, v2, vcc
	s_waitcnt lgkmcnt(6)
	v_add_f32_e32 v3, v3, v38
	v_cmp_lt_i32_e32 vcc, -1, v37
	v_mul_f32_e32 v3, 0x3fb8aa3b, v3
	s_and_b64 vcc, s[14:15], vcc
	v_cndmask_b32_e32 v3, v219, v3, vcc
	s_waitcnt lgkmcnt(5)
	v_add_f32_e32 v4, v4, v40
	v_cmp_lt_i32_e32 vcc, -1, v39
	v_mul_f32_e32 v4, 0x3fb8aa3b, v4
	s_and_b64 vcc, s[14:15], vcc
	v_cndmask_b32_e32 v4, v219, v4, vcc
	s_waitcnt lgkmcnt(4)
	v_add_f32_e32 v5, v5, v42
	v_cmp_lt_i32_e32 vcc, -1, v41
	v_mul_f32_e32 v5, 0x3fb8aa3b, v5
	s_and_b64 vcc, s[14:15], vcc
	v_cndmask_b32_e32 v5, v219, v5, vcc
	s_waitcnt lgkmcnt(3)
	v_add_f32_e32 v6, v6, v44
	v_cmp_lt_i32_e32 vcc, -1, v43
	v_mul_f32_e32 v6, 0x3fb8aa3b, v6
	s_and_b64 vcc, s[14:15], vcc
	v_cndmask_b32_e32 v6, v219, v6, vcc
	s_waitcnt lgkmcnt(2)
	v_add_f32_e32 v7, v7, v46
	v_cmp_lt_i32_e32 vcc, -1, v45
	v_mul_f32_e32 v7, 0x3fb8aa3b, v7
	s_and_b64 vcc, s[14:15], vcc
	v_cndmask_b32_e32 v7, v219, v7, vcc
	s_waitcnt lgkmcnt(1)
	v_add_f32_e32 v8, v8, v48
	v_cmp_lt_i32_e32 vcc, -1, v47
	v_mul_f32_e32 v8, 0x3fb8aa3b, v8
	s_and_b64 vcc, s[14:15], vcc
	v_subrev_u32_e32 v35, 48, v34
	v_subrev_u32_e32 v37, 49, v34
	v_subrev_u32_e32 v39, 50, v34
	v_subrev_u32_e32 v41, 51, v34
	v_subrev_u32_e32 v43, 56, v34
	v_subrev_u32_e32 v45, 57, v34
	v_subrev_u32_e32 v47, 58, v34
	v_subrev_u32_e32 v34, 59, v34
	v_cndmask_b32_e32 v8, v219, v8, vcc
	s_waitcnt lgkmcnt(0)
	v_add_f32_e32 v9, v9, v190
	v_cmp_lt_i32_e32 vcc, -1, v49
	v_med3_i32 v36, v35, 0, v220
	v_med3_i32 v38, v37, 0, v220
	v_med3_i32 v40, v39, 0, v220
	v_med3_i32 v42, v41, 0, v220
	v_med3_i32 v44, v43, 0, v220
	v_med3_i32 v46, v45, 0, v220
	v_med3_i32 v48, v47, 0, v220
	v_med3_i32 v49, v34, 0, v220
	v_mul_f32_e32 v9, 0x3fb8aa3b, v9
	s_and_b64 vcc, s[14:15], vcc
	v_lshl_add_u32 v36, v36, 2, v180
	v_lshl_add_u32 v38, v38, 2, v180
	v_lshl_add_u32 v40, v40, 2, v180
	v_lshl_add_u32 v42, v42, 2, v180
	v_lshl_add_u32 v44, v44, 2, v180
	v_lshl_add_u32 v46, v46, 2, v180
	v_lshl_add_u32 v48, v48, 2, v180
	v_lshl_add_u32 v49, v49, 2, v180
	v_cndmask_b32_e32 v9, v219, v9, vcc
	ds_read_b32 v36, v36
	ds_read_b32 v38, v38
	ds_read_b32 v40, v40
	ds_read_b32 v42, v42
	ds_read_b32 v44, v44
	ds_read_b32 v46, v46
	ds_read_b32 v48, v48
	ds_read_b32 v49, v49
	s_waitcnt lgkmcnt(7)
	v_add_f32_e32 v10, v10, v36
	v_cmp_lt_i32_e32 vcc, -1, v35
	v_mul_f32_e32 v10, 0x3fb8aa3b, v10
	s_and_b64 vcc, s[14:15], vcc
	v_cndmask_b32_e32 v10, v219, v10, vcc
	s_waitcnt lgkmcnt(6)
	v_add_f32_e32 v11, v11, v38
	v_cmp_lt_i32_e32 vcc, -1, v37
	v_mul_f32_e32 v11, 0x3fb8aa3b, v11
	s_and_b64 vcc, s[14:15], vcc
	v_cndmask_b32_e32 v11, v219, v11, vcc
	s_waitcnt lgkmcnt(5)
	v_add_f32_e32 v12, v12, v40
	v_cmp_lt_i32_e32 vcc, -1, v39
	v_mul_f32_e32 v12, 0x3fb8aa3b, v12
	s_and_b64 vcc, s[14:15], vcc
	v_cndmask_b32_e32 v12, v219, v12, vcc
	s_waitcnt lgkmcnt(4)
	v_add_f32_e32 v13, v13, v42
	v_cmp_lt_i32_e32 vcc, -1, v41
	v_mul_f32_e32 v13, 0x3fb8aa3b, v13
	s_and_b64 vcc, s[14:15], vcc
	v_cndmask_b32_e32 v13, v219, v13, vcc
	s_waitcnt lgkmcnt(3)
	v_add_f32_e32 v14, v14, v44
	v_cmp_lt_i32_e32 vcc, -1, v43
	v_mul_f32_e32 v14, 0x3fb8aa3b, v14
	s_and_b64 vcc, s[14:15], vcc
	v_cndmask_b32_e32 v14, v219, v14, vcc
	s_waitcnt lgkmcnt(2)
	v_add_f32_e32 v15, v15, v46
	v_cmp_lt_i32_e32 vcc, -1, v45
	v_mul_f32_e32 v15, 0x3fb8aa3b, v15
	s_and_b64 vcc, s[14:15], vcc
	v_cndmask_b32_e32 v15, v219, v15, vcc
	s_waitcnt lgkmcnt(1)
	v_add_f32_e32 v16, v16, v48
	v_cmp_lt_i32_e32 vcc, -1, v47
	v_mul_f32_e32 v16, 0x3fb8aa3b, v16
	s_and_b64 vcc, s[14:15], vcc
	v_cndmask_b32_e32 v16, v219, v16, vcc
	s_waitcnt lgkmcnt(0)
	v_add_f32_e32 v17, v17, v49
	v_cmp_lt_i32_e32 vcc, -1, v34
	v_mul_f32_e32 v17, 0x3fb8aa3b, v17
	s_and_b64 vcc, s[14:15], vcc
	v_cndmask_b32_e32 v17, v219, v17, vcc

.Lit_exp:
	v_cndmask_b32_e64 v35, v219, v208, s[14:15]
	v_sub_f32_e32 v35, v35, v140
	v_cndmask_b32_e64 v142, 1.0, v222, s[16:17]
	v_cndmask_b32_e64 v144, -v140, v35, s[16:17]
	v_pk_fma_f32 v[18:19], v[18:19], v[142:143], v[144:145] op_sel_hi:[1,0,0]
	v_pk_fma_f32 v[20:21], v[20:21], v[142:143], v[144:145] op_sel_hi:[1,0,0]
	v_pk_fma_f32 v[22:23], v[22:23], v[142:143], v[144:145] op_sel_hi:[1,0,0]
	v_pk_fma_f32 v[24:25], v[24:25], v[142:143], v[144:145] op_sel_hi:[1,0,0]
	v_exp_f32_e32 v18, v18
	v_exp_f32_e32 v19, v19
	v_exp_f32_e32 v20, v20
	v_exp_f32_e32 v21, v21
	v_exp_f32_e32 v22, v22
	v_exp_f32_e32 v23, v23
	v_exp_f32_e32 v24, v24
	v_exp_f32_e32 v25, v25
	v_pk_add_f32 v[132:133], v[18:19], v[20:21]
	v_pk_add_f32 v[132:133], v[132:133], v[22:23]
	v_pk_add_f32 v[132:133], v[132:133], v[24:25]
	v_cvt_pk_bf16_f32 v234, v18, v19
	v_cvt_pk_bf16_f32 v235, v20, v21
	v_cvt_pk_bf16_f32 v236, v22, v23
	v_cvt_pk_bf16_f32 v237, v24, v25
	v_pk_fma_f32 v[242:243], v[26:27], v[142:143], v[144:145] op_sel_hi:[1,0,0]
	v_pk_fma_f32 v[244:245], v[28:29], v[142:143], v[144:145] op_sel_hi:[1,0,0]
	v_pk_fma_f32 v[246:247], v[30:31], v[142:143], v[144:145] op_sel_hi:[1,0,0]
	v_pk_fma_f32 v[248:249], v[32:33], v[142:143], v[144:145] op_sel_hi:[1,0,0]
	v_mfma_f32_32x32x16_bf16 v[18:33], v[74:77], v[234:237], 0
	v_mfma_f32_32x32x16_bf16 v[34:49], v[94:97], v[234:237], 0
	v_exp_f32_e32 v242, v242
	v_exp_f32_e32 v243, v243
	v_exp_f32_e32 v244, v244
	v_exp_f32_e32 v245, v245
	v_exp_f32_e32 v246, v246
	v_exp_f32_e32 v247, v247
	v_exp_f32_e32 v248, v248
	v_exp_f32_e32 v249, v249
	v_pk_add_f32 v[132:133], v[132:133], v[242:243]
	v_pk_add_f32 v[132:133], v[132:133], v[244:245]
	v_pk_add_f32 v[132:133], v[132:133], v[246:247]
	v_pk_add_f32 v[132:133], v[132:133], v[248:249]
	v_cvt_pk_bf16_f32 v238, v242, v243
	v_cvt_pk_bf16_f32 v239, v244, v245
	v_cvt_pk_bf16_f32 v240, v246, v247
	v_cvt_pk_bf16_f32 v241, v248, v249
	v_pk_fma_f32 v[2:3], v[2:3], v[142:143], v[144:145] op_sel_hi:[1,0,0]
	v_pk_fma_f32 v[4:5], v[4:5], v[142:143], v[144:145] op_sel_hi:[1,0,0]
	v_pk_fma_f32 v[6:7], v[6:7], v[142:143], v[144:145] op_sel_hi:[1,0,0]
	v_pk_fma_f32 v[8:9], v[8:9], v[142:143], v[144:145] op_sel_hi:[1,0,0]
	v_mfma_f32_32x32x16_bf16 v[18:33], v[70:73], v[238:241], v[18:33]
	v_mfma_f32_32x32x16_bf16 v[34:49], v[102:105], v[238:241], v[34:49]
	v_exp_f32_e32 v2, v2
	v_exp_f32_e32 v3, v3
	v_exp_f32_e32 v4, v4
	v_exp_f32_e32 v5, v5
	v_exp_f32_e32 v6, v6
	v_exp_f32_e32 v7, v7
	v_exp_f32_e32 v8, v8
	v_exp_f32_e32 v9, v9
	v_pk_add_f32 v[132:133], v[132:133], v[2:3]
	v_pk_add_f32 v[132:133], v[132:133], v[4:5]
	v_pk_add_f32 v[132:133], v[132:133], v[6:7]
	v_pk_add_f32 v[132:133], v[132:133], v[8:9]
	v_cvt_pk_bf16_f32 v234, v2, v3
	v_cvt_pk_bf16_f32 v235, v4, v5
	v_cvt_pk_bf16_f32 v236, v6, v7
	v_cvt_pk_bf16_f32 v237, v8, v9
	v_pk_fma_f32 v[10:11], v[10:11], v[142:143], v[144:145] op_sel_hi:[1,0,0]
	v_pk_fma_f32 v[12:13], v[12:13], v[142:143], v[144:145] op_sel_hi:[1,0,0]
	v_pk_fma_f32 v[14:15], v[14:15], v[142:143], v[144:145] op_sel_hi:[1,0,0]
	v_pk_fma_f32 v[16:17], v[16:17], v[142:143], v[144:145] op_sel_hi:[1,0,0]
	v_mfma_f32_32x32x16_bf16 v[18:33], v[86:89], v[234:237], v[18:33]
	v_mfma_f32_32x32x16_bf16 v[34:49], v[106:109], v[234:237], v[34:49]
	v_exp_f32_e32 v10, v10
	v_exp_f32_e32 v11, v11
	v_exp_f32_e32 v12, v12
	v_exp_f32_e32 v13, v13
	v_exp_f32_e32 v14, v14
	v_exp_f32_e32 v15, v15
	v_exp_f32_e32 v16, v16
	v_exp_f32_e32 v17, v17
	v_pk_add_f32 v[132:133], v[132:133], v[10:11]
	v_pk_add_f32 v[132:133], v[132:133], v[12:13]
	v_pk_add_f32 v[132:133], v[132:133], v[14:15]
	v_pk_add_f32 v[132:133], v[132:133], v[16:17]
	v_cvt_pk_bf16_f32 v238, v10, v11
	v_cvt_pk_bf16_f32 v239, v12, v13
	v_cvt_pk_bf16_f32 v240, v14, v15
	v_cvt_pk_bf16_f32 v241, v16, v17
	s_nop 1
	v_mfma_f32_32x32x16_bf16 v[18:33], v[82:85], v[238:241], v[18:33]
	v_mfma_f32_32x32x16_bf16 v[34:49], v[110:113], v[238:241], v[34:49]
	v_add_f32_e32 v135, v132, v133
	v_mov_b32_e32 v2, v135
	s_nop 1
	v_permlane32_swap_b32_e32 v135, v2
	v_add_f32_e32 v2, v135, v2
	s_and_saveexec_b64 s[16:17], s[60:61]
	s_cbranch_execz .Lit_nols
	v_cvt_i32_f32_e32 v3, v2
	v_add_u32_e32 v4, 0x10800, v190
	ds_add_u32 v4, v3
